# grid barrier: every workgroup issues its acquire invalidate right behind its arrival atomic (counted vmcnt(1)); later invalidates removed; top-level last arriver releases every XCD directly
# speedup vs baseline: 1.0109x; 1.0009x over previous
; __device__ __forceinline__ unsigned xb_ld(unsigned* p)              { return __hip_atomic_load(p, __ATOMIC_RELAXED, __HIP_MEMORY_SCOPE_AGENT); }
; __device__ __forceinline__ unsigned xb_add(unsigned* p, unsigned v) { return __hip_atomic_fetch_add(p, v, __ATOMIC_RELAXED, __HIP_MEMORY_SCOPE_AGENT); }
; #define XB_SPIN(cond, bar) do { unsigned _sp = 0; while (cond) { __builtin_amdgcn_s_sleep(1); \
;     if ((++_sp & 255u) == 0u) { if (xb_ld(&(bar)[XB_TMO])) break; if (_sp > XB_SPIN_CAP) { atomicAdd(&(bar)[XB_TMO], 1u); break; } } } } while (0)
; __device__ __forceinline__ void xcd_barrier(unsigned* bar, volatile LAS unsigned* st, bool tid0) {
;     ...
;         const unsigned old = xb_add(&bar[XB_XSUB(x)], 1u);
;         const unsigned gen = old / nloc;
;         if (old + 1u == (gen + 1u) * nloc) {
;             __builtin_amdgcn_fence(__ATOMIC_RELEASE, "agent");
;             asm volatile("s_waitcnt vmcnt(0)" ::: "memory");
;             const unsigned og = xb_add(&bar[XB_TOP], 1u);
;             const unsigned tg = og / nx;
;             if (og + 1u == (tg + 1u) * nx) xb_add(&bar[XB_TOPGEN], 1u);
;             else XB_SPIN(xb_ld(&bar[XB_TOPGEN]) == tg, bar);
;             __builtin_amdgcn_fence(__ATOMIC_ACQUIRE, "agent");
;             xb_add(&bar[XB_XGEN(x)], 1u);
;             asm volatile("s_waitcnt vmcnt(0)" ::: "memory");
;         } else {
;             XB_SPIN(xb_ld(&bar[XB_XGEN(x)]) == gen, bar);
;             __builtin_amdgcn_fence(__ATOMIC_ACQUIRE, "agent");
;             asm volatile("s_waitcnt vmcnt(0)" ::: "memory");
.LBB0_47:
	s_or_b64 exec, exec, s[8:9]
	buffer_inv sc1
	v_cvt_f32_u32_e32 v5, v3
	s_waitcnt vmcnt(1)
	v_readfirstlane_b32 s2, v4
	v_sub_u32_e32 v4, 0, v3
	v_rcp_iflag_f32_e32 v5, v5
	v_add_u32_e32 v6, s2, v2
	v_mul_f32_e32 v5, 0x4f7ffffe, v5
	v_cvt_u32_f32_e32 v5, v5
	v_mul_lo_u32 v2, v4, v5
	v_mul_hi_u32 v2, v5, v2
	v_add_u32_e32 v2, v5, v2
	v_mul_hi_u32 v2, v6, v2
	v_mul_lo_u32 v4, v2, v3
	v_sub_u32_e32 v4, v6, v4
	v_add_u32_e32 v5, 1, v2
	v_cmp_ge_u32_e32 vcc, v4, v3
	s_nop 1
	v_cndmask_b32_e32 v2, v2, v5, vcc
	v_sub_u32_e32 v5, v4, v3
	v_cndmask_b32_e32 v4, v4, v5, vcc
	v_add_u32_e32 v5, 1, v2
	v_cmp_ge_u32_e32 vcc, v4, v3
	v_add_u32_e32 v4, 1, v6
	s_nop 0
	v_cndmask_b32_e32 v2, v2, v5, vcc
	v_mul_lo_u32 v5, v3, v2
	v_add_u32_e32 v3, v5, v3
	v_cmp_ne_u32_e32 vcc, v4, v3
	s_and_saveexec_b64 s[2:3], vcc
	s_xor_b64 s[6:7], exec, s[2:3]
	s_cbranch_execz .LBB0_61
	s_waitcnt lgkmcnt(0)
	v_mov_b32_e32 v1, 0x2000
	global_load_dword v1, v1, s[4:5] offset:1024 sc1
	s_add_u32 s10, s4, 0x2400
	s_addc_u32 s11, s5, 0
	s_waitcnt vmcnt(0)
	v_cmp_eq_u32_e32 vcc, v1, v2
	s_and_saveexec_b64 s[8:9], vcc
	s_cbranch_execz .LBB0_60
	s_mov_b32 s2, 1
	s_mov_b64 s[12:13], 0
	v_mov_b32_e32 v1, 0
	s_branch .LBB0_51

; __device__ __forceinline__ unsigned xb_ld(unsigned* p)              { return __hip_atomic_load(p, __ATOMIC_RELAXED, __HIP_MEMORY_SCOPE_AGENT); }
; __device__ __forceinline__ unsigned xb_add(unsigned* p, unsigned v) { return __hip_atomic_fetch_add(p, v, __ATOMIC_RELAXED, __HIP_MEMORY_SCOPE_AGENT); }
; #define XB_SPIN(cond, bar) do { unsigned _sp = 0; while (cond) { __builtin_amdgcn_s_sleep(1); \
;     if ((++_sp & 255u) == 0u) { if (xb_ld(&(bar)[XB_TMO])) break; if (_sp > XB_SPIN_CAP) { atomicAdd(&(bar)[XB_TMO], 1u); break; } } } } while (0)
; __device__ __forceinline__ void xcd_barrier(unsigned* bar, volatile LAS unsigned* st, bool tid0) {
;     ...
;         const unsigned old = xb_add(&bar[XB_XSUB(x)], 1u);
;         const unsigned gen = old / nloc;
;         if (old + 1u == (gen + 1u) * nloc) {
;             __builtin_amdgcn_fence(__ATOMIC_RELEASE, "agent");
;             asm volatile("s_waitcnt vmcnt(0)" ::: "memory");
;             const unsigned og = xb_add(&bar[XB_TOP], 1u);
;             const unsigned tg = og / nx;
;             if (og + 1u == (tg + 1u) * nx) xb_add(&bar[XB_TOPGEN], 1u);
;             else XB_SPIN(xb_ld(&bar[XB_TOPGEN]) == tg, bar);
;             __builtin_amdgcn_fence(__ATOMIC_ACQUIRE, "agent");
;             xb_add(&bar[XB_XGEN(x)], 1u);
;             asm volatile("s_waitcnt vmcnt(0)" ::: "memory");
;         } else {
;             XB_SPIN(xb_ld(&bar[XB_XGEN(x)]) == gen, bar);
;             __builtin_amdgcn_fence(__ATOMIC_ACQUIRE, "agent");
;             asm volatile("s_waitcnt vmcnt(0)" ::: "memory");
.LBB0_189:
	s_or_b64 exec, exec, s[8:9]
	buffer_inv sc1
	v_cvt_f32_u32_e32 v4, v2
	s_waitcnt vmcnt(1)
	v_readfirstlane_b32 s2, v3
	v_sub_u32_e32 v3, 0, v2
	v_rcp_iflag_f32_e32 v4, v4
	v_add_u32_e32 v5, s2, v1
	v_mul_f32_e32 v4, 0x4f7ffffe, v4
	v_cvt_u32_f32_e32 v4, v4
	v_mul_lo_u32 v1, v3, v4
	v_mul_hi_u32 v1, v4, v1
	v_add_u32_e32 v1, v4, v1
	v_mul_hi_u32 v1, v5, v1
	v_mul_lo_u32 v3, v1, v2
	v_sub_u32_e32 v3, v5, v3
	v_add_u32_e32 v4, 1, v1
	v_cmp_ge_u32_e32 vcc, v3, v2
	s_nop 1
	v_cndmask_b32_e32 v1, v1, v4, vcc
	v_sub_u32_e32 v4, v3, v2
	v_cndmask_b32_e32 v3, v3, v4, vcc
	v_add_u32_e32 v4, 1, v1
	v_cmp_ge_u32_e32 vcc, v3, v2
	v_add_u32_e32 v3, 1, v5
	s_nop 0
	v_cndmask_b32_e32 v1, v1, v4, vcc
	v_mul_lo_u32 v4, v2, v1
	v_add_u32_e32 v2, v4, v2
	v_cmp_ne_u32_e32 vcc, v3, v2
	s_and_saveexec_b64 s[2:3], vcc
	s_xor_b64 s[6:7], exec, s[2:3]
	s_cbranch_execz .LBB0_203
	s_waitcnt lgkmcnt(0)
	v_mov_b32_e32 v0, 0x2000
	global_load_dword v0, v0, s[4:5] offset:1024 sc1
	s_add_u32 s10, s4, 0x2400
	s_addc_u32 s11, s5, 0
	s_waitcnt vmcnt(0)
	v_cmp_eq_u32_e32 vcc, v0, v1
	s_and_saveexec_b64 s[8:9], vcc
	s_cbranch_execz .LBB0_202
	s_mov_b32 s2, 1
	s_mov_b64 s[12:13], 0
	v_mov_b32_e32 v0, 0
	s_branch .LBB0_193

; __device__ __forceinline__ unsigned xb_ld(unsigned* p)              { return __hip_atomic_load(p, __ATOMIC_RELAXED, __HIP_MEMORY_SCOPE_AGENT); }
; __device__ __forceinline__ unsigned xb_add(unsigned* p, unsigned v) { return __hip_atomic_fetch_add(p, v, __ATOMIC_RELAXED, __HIP_MEMORY_SCOPE_AGENT); }
; #define XB_SPIN(cond, bar) do { unsigned _sp = 0; while (cond) { __builtin_amdgcn_s_sleep(1); \
;     if ((++_sp & 255u) == 0u) { if (xb_ld(&(bar)[XB_TMO])) break; if (_sp > XB_SPIN_CAP) { atomicAdd(&(bar)[XB_TMO], 1u); break; } } } } while (0)
; __device__ __forceinline__ void xcd_barrier(unsigned* bar, volatile LAS unsigned* st, bool tid0) {
;     ...
;         const unsigned old = xb_add(&bar[XB_XSUB(x)], 1u);
;         const unsigned gen = old / nloc;
;         if (old + 1u == (gen + 1u) * nloc) {
;             __builtin_amdgcn_fence(__ATOMIC_RELEASE, "agent");
;             asm volatile("s_waitcnt vmcnt(0)" ::: "memory");
;             const unsigned og = xb_add(&bar[XB_TOP], 1u);
;             const unsigned tg = og / nx;
;             if (og + 1u == (tg + 1u) * nx) xb_add(&bar[XB_TOPGEN], 1u);
;             else XB_SPIN(xb_ld(&bar[XB_TOPGEN]) == tg, bar);
;             __builtin_amdgcn_fence(__ATOMIC_ACQUIRE, "agent");
;             xb_add(&bar[XB_XGEN(x)], 1u);
;             asm volatile("s_waitcnt vmcnt(0)" ::: "memory");
;         } else {
;             XB_SPIN(xb_ld(&bar[XB_XGEN(x)]) == gen, bar);
;             __builtin_amdgcn_fence(__ATOMIC_ACQUIRE, "agent");
;             asm volatile("s_waitcnt vmcnt(0)" ::: "memory");
.LBB0_253:
	s_or_b64 exec, exec, s[8:9]
	buffer_inv sc1
	v_cvt_f32_u32_e32 v4, v2
	s_waitcnt vmcnt(1)
	v_readfirstlane_b32 s3, v3
	v_sub_u32_e32 v3, 0, v2
	v_rcp_iflag_f32_e32 v4, v4
	v_add_u32_e32 v5, s3, v1
	v_mul_f32_e32 v4, 0x4f7ffffe, v4
	v_cvt_u32_f32_e32 v4, v4
	v_mul_lo_u32 v1, v3, v4
	v_mul_hi_u32 v1, v4, v1
	v_add_u32_e32 v1, v4, v1
	v_mul_hi_u32 v1, v5, v1
	v_mul_lo_u32 v3, v1, v2
	v_sub_u32_e32 v3, v5, v3
	v_add_u32_e32 v4, 1, v1
	v_cmp_ge_u32_e32 vcc, v3, v2
	s_nop 1
	v_cndmask_b32_e32 v1, v1, v4, vcc
	v_sub_u32_e32 v4, v3, v2
	v_cndmask_b32_e32 v3, v3, v4, vcc
	v_add_u32_e32 v4, 1, v1
	v_cmp_ge_u32_e32 vcc, v3, v2
	v_add_u32_e32 v3, 1, v5
	s_nop 0
	v_cndmask_b32_e32 v1, v1, v4, vcc
	v_mul_lo_u32 v4, v2, v1
	v_add_u32_e32 v2, v4, v2
	v_cmp_ne_u32_e32 vcc, v3, v2
	s_and_saveexec_b64 s[6:7], vcc
	s_xor_b64 s[6:7], exec, s[6:7]
	s_cbranch_execz .LBB0_267
	s_waitcnt lgkmcnt(0)
	v_mov_b32_e32 v0, 0x2000
	global_load_dword v0, v0, s[4:5] offset:1024 sc1
	s_add_u32 s10, s4, 0x2400
	s_addc_u32 s11, s5, 0
	s_waitcnt vmcnt(0)
	v_cmp_eq_u32_e32 vcc, v0, v1
	s_and_saveexec_b64 s[8:9], vcc
	s_cbranch_execz .LBB0_266
	s_mov_b32 s3, 1
	s_mov_b64 s[16:17], 0
	v_mov_b32_e32 v0, 0
	s_branch .LBB0_257

; __device__ __forceinline__ unsigned xb_ld(unsigned* p)              { return __hip_atomic_load(p, __ATOMIC_RELAXED, __HIP_MEMORY_SCOPE_AGENT); }
; __device__ __forceinline__ unsigned xb_add(unsigned* p, unsigned v) { return __hip_atomic_fetch_add(p, v, __ATOMIC_RELAXED, __HIP_MEMORY_SCOPE_AGENT); }
; #define XB_SPIN(cond, bar) do { unsigned _sp = 0; while (cond) { __builtin_amdgcn_s_sleep(1); \
;     if ((++_sp & 255u) == 0u) { if (xb_ld(&(bar)[XB_TMO])) break; if (_sp > XB_SPIN_CAP) { atomicAdd(&(bar)[XB_TMO], 1u); break; } } } } while (0)
; __device__ __forceinline__ void xcd_barrier(unsigned* bar, volatile LAS unsigned* st, bool tid0) {
;     ...
;         const unsigned old = xb_add(&bar[XB_XSUB(x)], 1u);
;         const unsigned gen = old / nloc;
;         if (old + 1u == (gen + 1u) * nloc) {
;             __builtin_amdgcn_fence(__ATOMIC_RELEASE, "agent");
;             asm volatile("s_waitcnt vmcnt(0)" ::: "memory");
;             const unsigned og = xb_add(&bar[XB_TOP], 1u);
;             const unsigned tg = og / nx;
;             if (og + 1u == (tg + 1u) * nx) xb_add(&bar[XB_TOPGEN], 1u);
;             else XB_SPIN(xb_ld(&bar[XB_TOPGEN]) == tg, bar);
;             __builtin_amdgcn_fence(__ATOMIC_ACQUIRE, "agent");
;             xb_add(&bar[XB_XGEN(x)], 1u);
;             asm volatile("s_waitcnt vmcnt(0)" ::: "memory");
;         } else {
;             XB_SPIN(xb_ld(&bar[XB_XGEN(x)]) == gen, bar);
;             __builtin_amdgcn_fence(__ATOMIC_ACQUIRE, "agent");
;             asm volatile("s_waitcnt vmcnt(0)" ::: "memory");
.LBB0_570:
	s_or_b64 exec, exec, s[12:13]
	buffer_inv sc1
	v_cvt_f32_u32_e32 v4, v2
	s_waitcnt vmcnt(1)
	v_readfirstlane_b32 s2, v3
	v_sub_u32_e32 v3, 0, v2
	v_rcp_iflag_f32_e32 v4, v4
	v_add_u32_e32 v5, s2, v1
	v_mul_f32_e32 v4, 0x4f7ffffe, v4
	v_cvt_u32_f32_e32 v4, v4
	v_mul_lo_u32 v1, v3, v4
	v_mul_hi_u32 v1, v4, v1
	v_add_u32_e32 v1, v4, v1
	v_mul_hi_u32 v1, v5, v1
	v_mul_lo_u32 v3, v1, v2
	v_sub_u32_e32 v3, v5, v3
	v_add_u32_e32 v4, 1, v1
	v_cmp_ge_u32_e32 vcc, v3, v2
	s_nop 1
	v_cndmask_b32_e32 v1, v1, v4, vcc
	v_sub_u32_e32 v4, v3, v2
	v_cndmask_b32_e32 v3, v3, v4, vcc
	v_add_u32_e32 v4, 1, v1
	v_cmp_ge_u32_e32 vcc, v3, v2
	v_add_u32_e32 v3, 1, v5
	s_nop 0
	v_cndmask_b32_e32 v1, v1, v4, vcc
	v_mul_lo_u32 v4, v2, v1
	v_add_u32_e32 v2, v4, v2
	v_cmp_ne_u32_e32 vcc, v3, v2
	s_and_saveexec_b64 s[2:3], vcc
	s_xor_b64 s[10:11], exec, s[2:3]
	s_cbranch_execz .LBB0_584
	s_waitcnt lgkmcnt(0)
	v_mov_b32_e32 v0, 0x2000
	global_load_dword v0, v0, s[6:7] offset:1024 sc1
	s_add_u32 s14, s6, 0x2400
	s_addc_u32 s15, s7, 0
	s_waitcnt vmcnt(0)
	v_cmp_eq_u32_e32 vcc, v0, v1
	s_and_saveexec_b64 s[12:13], vcc
	s_cbranch_execz .LBB0_583
	s_mov_b32 s2, 1
	s_mov_b64 s[16:17], 0
	v_mov_b32_e32 v0, 0
	s_branch .LBB0_574

; __device__ __forceinline__ unsigned xb_ld(unsigned* p)              { return __hip_atomic_load(p, __ATOMIC_RELAXED, __HIP_MEMORY_SCOPE_AGENT); }
; __device__ __forceinline__ unsigned xb_add(unsigned* p, unsigned v) { return __hip_atomic_fetch_add(p, v, __ATOMIC_RELAXED, __HIP_MEMORY_SCOPE_AGENT); }
; #define XB_SPIN(cond, bar) do { unsigned _sp = 0; while (cond) { __builtin_amdgcn_s_sleep(1); \
;     if ((++_sp & 255u) == 0u) { if (xb_ld(&(bar)[XB_TMO])) break; if (_sp > XB_SPIN_CAP) { atomicAdd(&(bar)[XB_TMO], 1u); break; } } } } while (0)
; __device__ __forceinline__ void xcd_barrier(unsigned* bar, volatile LAS unsigned* st, bool tid0) {
;     ...
;         if (nloc == 0u) { xcd_barrier_complete(bar, x, nloc, nx); st[0] = nloc; st[1] = nx; }
;         const unsigned old = xb_add(&bar[XB_XSUB(x)], 1u);
;         const unsigned gen = old / nloc;
;         if (old + 1u == (gen + 1u) * nloc) {
;             __builtin_amdgcn_fence(__ATOMIC_RELEASE, "agent");
;             asm volatile("s_waitcnt vmcnt(0)" ::: "memory");
;             const unsigned og = xb_add(&bar[XB_TOP], 1u);
;             const unsigned tg = og / nx;
;             if (og + 1u == (tg + 1u) * nx) xb_add(&bar[XB_TOPGEN], 1u);
;             else XB_SPIN(xb_ld(&bar[XB_TOPGEN]) == tg, bar);
;             __builtin_amdgcn_fence(__ATOMIC_ACQUIRE, "agent");
;             xb_add(&bar[XB_XGEN(x)], 1u);
;             asm volatile("s_waitcnt vmcnt(0)" ::: "memory");
;         } else {
;             XB_SPIN(xb_ld(&bar[XB_XGEN(x)]) == gen, bar);
;             __builtin_amdgcn_fence(__ATOMIC_ACQUIRE, "agent");
;             asm volatile("s_waitcnt vmcnt(0)" ::: "memory");
.LBB0_661:
	s_or_b64 exec, exec, s[12:13]
	buffer_inv sc1
	v_cvt_f32_u32_e32 v4, v2
	s_waitcnt vmcnt(1)
	v_readfirstlane_b32 s2, v3
	v_sub_u32_e32 v3, 0, v2
	v_rcp_iflag_f32_e32 v4, v4
	v_add_u32_e32 v5, s2, v1
	v_mul_f32_e32 v4, 0x4f7ffffe, v4
	v_cvt_u32_f32_e32 v4, v4
	v_mul_lo_u32 v1, v3, v4
	v_mul_hi_u32 v1, v4, v1
	v_add_u32_e32 v1, v4, v1
	v_mul_hi_u32 v1, v5, v1
	v_mul_lo_u32 v3, v1, v2
	v_sub_u32_e32 v3, v5, v3
	v_add_u32_e32 v4, 1, v1
	v_cmp_ge_u32_e32 vcc, v3, v2
	s_nop 1
	v_cndmask_b32_e32 v1, v1, v4, vcc
	v_sub_u32_e32 v4, v3, v2
	v_cndmask_b32_e32 v3, v3, v4, vcc
	v_add_u32_e32 v4, 1, v1
	v_cmp_ge_u32_e32 vcc, v3, v2
	v_add_u32_e32 v3, 1, v5
	s_nop 0
	v_cndmask_b32_e32 v1, v1, v4, vcc
	v_mul_lo_u32 v4, v2, v1
	v_add_u32_e32 v2, v4, v2
	v_cmp_ne_u32_e32 vcc, v3, v2
	s_and_saveexec_b64 s[2:3], vcc
	s_xor_b64 s[8:9], exec, s[2:3]
	s_cbranch_execz .LBB0_675
	s_waitcnt lgkmcnt(0)
	v_mov_b32_e32 v0, 0x2000
	global_load_dword v0, v0, s[6:7] offset:1024 sc1
	s_add_u32 s14, s6, 0x2400
	s_addc_u32 s15, s7, 0
	s_waitcnt vmcnt(0)
	v_cmp_eq_u32_e32 vcc, v0, v1
	s_and_saveexec_b64 s[12:13], vcc
	s_cbranch_execz .LBB0_674
	s_mov_b32 s2, 1
	s_mov_b64 s[16:17], 0
	v_mov_b32_e32 v0, 0
	s_branch .LBB0_665

; __device__ __forceinline__ unsigned xb_ld(unsigned* p)              { return __hip_atomic_load(p, __ATOMIC_RELAXED, __HIP_MEMORY_SCOPE_AGENT); }
; __device__ __forceinline__ unsigned xb_add(unsigned* p, unsigned v) { return __hip_atomic_fetch_add(p, v, __ATOMIC_RELAXED, __HIP_MEMORY_SCOPE_AGENT); }
; #define XB_SPIN(cond, bar) do { unsigned _sp = 0; while (cond) { __builtin_amdgcn_s_sleep(1); \
;     if ((++_sp & 255u) == 0u) { if (xb_ld(&(bar)[XB_TMO])) break; if (_sp > XB_SPIN_CAP) { atomicAdd(&(bar)[XB_TMO], 1u); break; } } } } while (0)
; __device__ __forceinline__ void xcd_barrier(unsigned* bar, volatile LAS unsigned* st, bool tid0) {
;     ...
;         if (nloc == 0u) { xcd_barrier_complete(bar, x, nloc, nx); st[0] = nloc; st[1] = nx; }
;         const unsigned old = xb_add(&bar[XB_XSUB(x)], 1u);
;         const unsigned gen = old / nloc;
;         if (old + 1u == (gen + 1u) * nloc) {
;             __builtin_amdgcn_fence(__ATOMIC_RELEASE, "agent");
;             asm volatile("s_waitcnt vmcnt(0)" ::: "memory");
;             const unsigned og = xb_add(&bar[XB_TOP], 1u);
;             const unsigned tg = og / nx;
;             if (og + 1u == (tg + 1u) * nx) xb_add(&bar[XB_TOPGEN], 1u);
;             else XB_SPIN(xb_ld(&bar[XB_TOPGEN]) == tg, bar);
;             __builtin_amdgcn_fence(__ATOMIC_ACQUIRE, "agent");
;             xb_add(&bar[XB_XGEN(x)], 1u);
;             asm volatile("s_waitcnt vmcnt(0)" ::: "memory");
;         } else {
;             XB_SPIN(xb_ld(&bar[XB_XGEN(x)]) == gen, bar);
;             __builtin_amdgcn_fence(__ATOMIC_ACQUIRE, "agent");
;             asm volatile("s_waitcnt vmcnt(0)" ::: "memory");
.LBB0_788:
	s_or_b64 exec, exec, s[14:15]
	buffer_inv sc1
	v_cvt_f32_u32_e32 v4, v2
	s_waitcnt vmcnt(1)
	v_readfirstlane_b32 s2, v3
	v_sub_u32_e32 v3, 0, v2
	v_rcp_iflag_f32_e32 v4, v4
	v_add_u32_e32 v5, s2, v1
	v_mul_f32_e32 v4, 0x4f7ffffe, v4
	v_cvt_u32_f32_e32 v4, v4
	v_mul_lo_u32 v1, v3, v4
	v_mul_hi_u32 v1, v4, v1
	v_add_u32_e32 v1, v4, v1
	v_mul_hi_u32 v1, v5, v1
	v_mul_lo_u32 v3, v1, v2
	v_sub_u32_e32 v3, v5, v3
	v_add_u32_e32 v4, 1, v1
	v_cmp_ge_u32_e32 vcc, v3, v2
	s_nop 1
	v_cndmask_b32_e32 v1, v1, v4, vcc
	v_sub_u32_e32 v4, v3, v2
	v_cndmask_b32_e32 v3, v3, v4, vcc
	v_add_u32_e32 v4, 1, v1
	v_cmp_ge_u32_e32 vcc, v3, v2
	v_add_u32_e32 v3, 1, v5
	s_nop 0
	v_cndmask_b32_e32 v1, v1, v4, vcc
	v_mul_lo_u32 v4, v2, v1
	v_add_u32_e32 v2, v4, v2
	v_cmp_ne_u32_e32 vcc, v3, v2
	s_and_saveexec_b64 s[2:3], vcc
	s_xor_b64 s[8:9], exec, s[2:3]
	s_cbranch_execz .LBB0_802
	s_waitcnt lgkmcnt(0)
	v_mov_b32_e32 v0, 0x2000
	global_load_dword v0, v0, s[6:7] offset:1024 sc1
	s_add_u32 s16, s6, 0x2400
	s_addc_u32 s17, s7, 0
	s_waitcnt vmcnt(0)
	v_cmp_eq_u32_e32 vcc, v0, v1
	s_and_saveexec_b64 s[14:15], vcc
	s_cbranch_execz .LBB0_801
	s_mov_b32 s2, 1
	s_mov_b64 s[18:19], 0
	v_mov_b32_e32 v0, 0
	s_branch .LBB0_792

; __device__ __forceinline__ unsigned xb_ld(unsigned* p)              { return __hip_atomic_load(p, __ATOMIC_RELAXED, __HIP_MEMORY_SCOPE_AGENT); }
; __device__ __forceinline__ unsigned xb_add(unsigned* p, unsigned v) { return __hip_atomic_fetch_add(p, v, __ATOMIC_RELAXED, __HIP_MEMORY_SCOPE_AGENT); }
; #define XB_SPIN(cond, bar) do { unsigned _sp = 0; while (cond) { __builtin_amdgcn_s_sleep(1); \
;     if ((++_sp & 255u) == 0u) { if (xb_ld(&(bar)[XB_TMO])) break; if (_sp > XB_SPIN_CAP) { atomicAdd(&(bar)[XB_TMO], 1u); break; } } } } while (0)
; __device__ __forceinline__ void xcd_barrier(unsigned* bar, volatile LAS unsigned* st, bool tid0) {
;     ...
;         if (nloc == 0u) { xcd_barrier_complete(bar, x, nloc, nx); st[0] = nloc; st[1] = nx; }
;         const unsigned old = xb_add(&bar[XB_XSUB(x)], 1u);
;         const unsigned gen = old / nloc;
;         if (old + 1u == (gen + 1u) * nloc) {
;             __builtin_amdgcn_fence(__ATOMIC_RELEASE, "agent");
;             asm volatile("s_waitcnt vmcnt(0)" ::: "memory");
;             const unsigned og = xb_add(&bar[XB_TOP], 1u);
;             const unsigned tg = og / nx;
;             if (og + 1u == (tg + 1u) * nx) xb_add(&bar[XB_TOPGEN], 1u);
;             else XB_SPIN(xb_ld(&bar[XB_TOPGEN]) == tg, bar);
;             __builtin_amdgcn_fence(__ATOMIC_ACQUIRE, "agent");
;             xb_add(&bar[XB_XGEN(x)], 1u);
;             asm volatile("s_waitcnt vmcnt(0)" ::: "memory");
;         } else {
;             XB_SPIN(xb_ld(&bar[XB_XGEN(x)]) == gen, bar);
;             __builtin_amdgcn_fence(__ATOMIC_ACQUIRE, "agent");
;             asm volatile("s_waitcnt vmcnt(0)" ::: "memory");
.LBB0_1050:
	s_or_b64 exec, exec, s[6:7]
	buffer_inv sc1
	v_cvt_f32_u32_e32 v4, v2
	s_waitcnt vmcnt(1)
	v_readfirstlane_b32 s4, v3
	v_sub_u32_e32 v3, 0, v2
	v_rcp_iflag_f32_e32 v4, v4
	v_add_u32_e32 v5, s4, v1
	v_mul_f32_e32 v4, 0x4f7ffffe, v4
	v_cvt_u32_f32_e32 v4, v4
	v_mul_lo_u32 v1, v3, v4
	v_mul_hi_u32 v1, v4, v1
	v_add_u32_e32 v1, v4, v1
	v_mul_hi_u32 v1, v5, v1
	v_mul_lo_u32 v3, v1, v2
	v_sub_u32_e32 v3, v5, v3
	v_add_u32_e32 v4, 1, v1
	v_cmp_ge_u32_e32 vcc, v3, v2
	s_nop 1
	v_cndmask_b32_e32 v1, v1, v4, vcc
	v_sub_u32_e32 v4, v3, v2
	v_cndmask_b32_e32 v3, v3, v4, vcc
	v_add_u32_e32 v4, 1, v1
	v_cmp_ge_u32_e32 vcc, v3, v2
	v_add_u32_e32 v3, 1, v5
	s_nop 0
	v_cndmask_b32_e32 v1, v1, v4, vcc
	v_mul_lo_u32 v4, v2, v1
	v_add_u32_e32 v2, v4, v2
	v_cmp_ne_u32_e32 vcc, v3, v2
	s_and_saveexec_b64 s[4:5], vcc
	s_xor_b64 s[4:5], exec, s[4:5]
	s_cbranch_execz .LBB0_1064
	s_waitcnt lgkmcnt(0)
	v_mov_b32_e32 v0, 0x2000
	global_load_dword v0, v0, s[2:3] offset:1024 sc1
	s_add_u32 s8, s2, 0x2400
	s_addc_u32 s9, s3, 0
	s_waitcnt vmcnt(0)
	v_cmp_eq_u32_e32 vcc, v0, v1
	s_and_saveexec_b64 s[6:7], vcc
	s_cbranch_execz .LBB0_1063
	s_mov_b32 s22, 1
	s_mov_b64 s[12:13], 0
	v_mov_b32_e32 v0, 0
	s_branch .LBB0_1054
